# phase-1 xBC conv epilogue rewritten by hand on the row-permuted A tile (conv taps register-local); plain/dt paths use re-defined row registers
# speedup vs baseline: 1.0414x; 1.0097x over previous
.LBB0_387:
	s_waitcnt lgkmcnt(0)
	s_load_dword s10, s[80:81], 0x0
	s_andn2_b64 vcc, exec, s[38:39]
	s_cbranch_vccnz .LBB0_502
	v_ashrrev_i32_e32 v0, 31, v2
	v_lshrrev_b32_e32 v0, 26, v0
	v_add_u32_e32 v0, v2, v0
	s_waitcnt vmcnt(0)
	v_ashrrev_i32_e32 v12, 6, v0
	v_bfe_i32 v0, v2, 27, 1
	v_lshlrev_b32_e32 v1, 4, v2
	v_lshrrev_b32_e32 v0, 22, v0
	v_add_u32_e32 v0, v1, v0
	v_and_b32_e32 v0, 0xfffffc00, v0
	v_sub_u32_e32 v0, v1, v0
	v_lshrrev_b32_e32 v4, 4, v0
	v_bitop3_b32 v4, v4, v0, 32 bitop3:0x6c
	v_ashrrev_i32_e32 v0, 31, v0
	v_lshrrev_b32_e32 v0, 26, v0
	v_add_u32_e32 v0, v4, v0
	v_ashrrev_i32_e32 v13, 6, v0
	v_lshlrev_b32_e32 v5, 3, v12
	v_mul_i32_i24_e32 v6, 64, v13
	v_and_b32_e32 v5, -16, v5
	v_sub_u32_e32 v4, v4, v6
	v_add_u32_e32 v0, v13, v5
	v_ashrrev_i16_sdwa v4, v221, sext(v4) dst_sel:DWORD dst_unused:UNUSED_PAD src0_sel:DWORD src1_sel:BYTE_0
	v_lshlrev_b32_e32 v5, 5, v12
	v_bfe_i32 v14, v4, 0, 16
	v_lshlrev_b32_e32 v4, 1, v0
	v_lshrrev_b32_e32 v6, 2, v0
	v_and_b32_e32 v7, 3, v13
	s_mov_b32 s2, 0x1fffe0
	v_and_b32_e32 v5, 32, v5
	v_and_b32_e32 v4, 24, v4
	v_and_b32_e32 v6, 4, v6
	v_and_or_b32 v7, v0, s2, v7
	v_or3_b32 v4, v7, v6, v4
	v_add_lshl_u32 v5, v5, v14, 1
	v_add_u32_e32 v1, 0x2000, v1
	v_lshl_add_u32 v176, v4, 11, v5
	v_ashrrev_i32_e32 v4, 31, v1
	v_lshrrev_b32_e32 v4, 22, v4
	v_add_u32_e32 v4, v1, v4
	v_ashrrev_i32_e32 v15, 10, v4
	v_mul_i32_i24_e32 v4, 0x400, v15
	v_sub_u32_e32 v1, v1, v4
	v_lshrrev_b32_e32 v4, 4, v1
	v_bitop3_b32 v1, v4, v1, 32 bitop3:0x6c
	v_lshl_add_u32 v0, v0, 11, v5
	v_bfe_u32 v20, v0, 11, 4
	v_bfe_u32 v21, v0, 15, 2
	v_and_b32_e32 v0, 0xfffe07ff, v0
	v_lshl_or_b32 v0, v20, 13, v0
	v_lshl_or_b32 v0, v21, 11, v0
	v_ashrrev_i32_e32 v5, 31, v1
	v_lshrrev_b32_e32 v5, 26, v5
	v_add_u32_e32 v5, v1, v5
	v_lshlrev_b32_e32 v4, 3, v15
	v_ashrrev_i32_e32 v16, 6, v5
	v_and_b32_e32 v5, 0xc0, v5
	v_and_b32_e32 v4, -16, v4
	v_sub_u32_e32 v1, v1, v5
	s_ashr_i32 s21, s20, 6
	v_add_u32_e32 v4, v16, v4
	v_ashrrev_i16_sdwa v1, v221, sext(v1) dst_sel:DWORD dst_unused:UNUSED_PAD src0_sel:DWORD src1_sel:BYTE_0
	v_lshlrev_b32_e32 v6, 5, v15
	v_bfe_i32 v17, v1, 0, 16
	v_lshlrev_b32_e32 v1, 1, v4
	v_lshrrev_b32_e32 v5, 2, v4
	v_and_b32_e32 v7, 3, v16
	s_lshl_b32 s67, s21, 10
	v_and_b32_e32 v6, 32, v6
	v_and_b32_e32 v1, 24, v1
	v_and_b32_e32 v5, 4, v5
	v_and_or_b32 v7, v4, s2, v7
	s_add_i32 s74, s67, 0
	v_or3_b32 v1, v7, v5, v1
	v_add_lshl_u32 v5, v6, v17, 1
	s_add_i32 m0, s74, 0x10000
	v_lshl_add_u32 v180, v1, 11, v5
	global_load_lds_dwordx4 v176, s[44:45]
	s_add_i32 m0, s74, 0x12000
	s_ashr_i32 s22, s20, 8
	global_load_lds_dwordx4 v180, s[44:45]
	s_mov_b32 m0, s74
	s_add_i32 s75, s74, 0x2000
	v_lshl_add_u32 v178, v4, 11, v5
	v_bfe_u32 v20, v178, 11, 4
	v_bfe_u32 v21, v178, 15, 2
	v_and_b32_e32 v178, 0xfffe07ff, v178
	v_lshl_or_b32 v178, v20, 13, v178
	v_lshl_or_b32 v178, v21, 11, v178
	global_load_lds_dwordx4 v0, s[0:1]
	s_mov_b32 m0, s75
	s_add_u32 s24, s44, 0x40000
	global_load_lds_dwordx4 v178, s[0:1]
	s_addc_u32 s25, s45, 0
	s_add_i32 m0, s74, 0x14000
	v_mov_b32_e32 v177, v3
	global_load_lds_dwordx4 v176, s[24:25]
	s_add_i32 m0, s74, 0x16000
	v_mov_b32_e32 v181, v3
	global_load_lds_dwordx4 v180, s[24:25]
	s_add_u32 s24, s0, 0x40000
	s_addc_u32 s25, s1, 0
	s_add_i32 s82, s74, 0x4000
	s_mov_b32 m0, s82
	s_add_i32 s83, s74, 0x6000
	global_load_lds_dwordx4 v0, s[24:25]
	s_mov_b32 m0, s83
	v_mov_b32_e32 v1, v3
	global_load_lds_dwordx4 v178, s[24:25]
	v_mov_b32_e32 v179, v3
	s_mov_b64 s[8:9], 0x6000
	s_mov_b64 s[6:7], 0x3000
	v_mov_b32_e32 v199, 1
	v_lshl_add_u64 v[10:11], s[44:45], 0, v[176:177]
	v_lshl_add_u64 v[8:9], s[44:45], 0, v[180:181]
	v_lshl_add_u64 v[6:7], s[0:1], 0, v[0:1]
	s_cmp_lg_u32 s22, 1
	v_lshl_add_u64 v[4:5], s[0:1], 0, v[178:179]
	s_cbranch_scc1 .LBB0_390
	s_barrier
.LBB0_390:
	s_and_b32 s21, s21, 3
	s_add_i32 m0, s74, 0x18000
	v_lshl_add_u64 v[10:11], v[10:11], 0, s[76:77]
	s_lshl_b32 s11, s22, 6
	s_lshl_b32 s24, s22, 13
	s_lshl_b32 s49, s21, 5
	s_lshl_b32 s25, s21, 12
	s_waitcnt vmcnt(4)
	s_barrier
	global_load_lds_dwordx4 v[10:11], off
	v_lshl_add_u64 v[8:9], v[8:9], 0, s[76:77]
	s_add_i32 m0, s74, 0x1a000
	s_add_i32 s48, s74, 0x8000
	s_add_i32 s50, s74, 0xa000
	global_load_lds_dwordx4 v[8:9], off
	v_lshl_add_u64 v[6:7], v[6:7], 0, s[76:77]
	s_mov_b32 m0, s48
	s_add_u32 s22, s44, 0x40080
	global_load_lds_dwordx4 v[6:7], off
	v_lshl_add_u64 v[4:5], v[4:5], 0, s[76:77]
	s_mov_b32 m0, s50
	s_addc_u32 s23, s45, 0
	global_load_lds_dwordx4 v[4:5], off
	s_add_i32 m0, s74, 0x1c000
	v_lshl_add_u64 v[4:5], s[22:23], 0, v[176:177]
	global_load_lds_dwordx4 v[4:5], off
	v_lshl_add_u64 v[4:5], s[22:23], 0, v[180:181]
	s_add_i32 m0, s74, 0x1e000
	v_and_b32_e32 v183, 15, v2
	global_load_lds_dwordx4 v[4:5], off
	v_lshrrev_b32_e32 v4, 1, v2
	v_and_b32_e32 v182, 24, v4
	v_lshlrev_b32_e32 v4, 1, v182
	v_lshlrev_b32_e32 v2, 2, v2
	s_cmp_eq_u32 s21, 0
	v_lshl_or_b32 v4, v183, 6, v4
	v_and_b32_e32 v2, 32, v2
	s_cselect_b64 s[36:37], -1, 0
	s_cmpk_lt_u32 s20, 0x100
	v_bitop3_b32 v6, v4, s24, v2 bitop3:0xde
	v_bitop3_b32 v187, v4, s25, v2 bitop3:0xde
	s_cselect_b64 s[2:3], -1, 0
	v_readlane_b32 s12, v254, 42
	v_writelane_b32 v255, s2, 3
	v_readlane_b32 s20, v254, 50
	v_readlane_b32 s21, v254, 51
	v_or_b32_e32 v2, s49, v182
	v_writelane_b32 v255, s3, 4
	v_readlane_b32 s20, v252, 52
	v_or_b32_e32 v201, 0xfffff800, v2
	v_lshlrev_b32_e32 v2, 2, v182
	v_readlane_b32 s24, v254, 54
	v_readlane_b32 s25, v254, 55
	v_readlane_b32 s21, v252, 53
	v_readlane_b32 s2, v255, 1
	v_lshl_add_u64 v[188:189], s[24:25], 0, v[2:3]
	v_lshl_add_u64 v[190:191], s[20:21], 0, v[2:3]
	v_readlane_b32 s3, v255, 2
	v_lshlrev_b32_e32 v2, 14, v12
	v_add_u32_e32 v184, -13, v183
	v_mov_b64_e32 v[4:5], s[2:3]
	v_and_b32_e32 v2, 0xffff8000, v2
	v_mad_u64_u32 v[192:193], s[20:21], v184, s68, v[4:5]
	v_lshl_add_u32 v2, v13, 11, v2
	v_and_b32_e32 v4, 1, v12
	v_lshl_or_b32 v2, v4, 6, v2
	v_lshl_add_u32 v194, v14, 1, v2
	v_bfe_u32 v20, v194, 11, 4
	v_bfe_u32 v21, v194, 15, 2
	v_and_b32_e32 v194, 0xfffe07ff, v194
	v_lshl_or_b32 v194, v20, 13, v194
	v_lshl_or_b32 v194, v21, 11, v194
	v_lshlrev_b32_e32 v2, 14, v15
	v_and_b32_e32 v2, 0xffff8000, v2
	s_waitcnt vmcnt(6)
	v_lshl_add_u32 v2, v16, 11, v2
	v_and_b32_e32 v4, 1, v15
	v_lshl_or_b32 v185, v183, 2, s11
	v_lshl_or_b32 v2, v4, 6, v2
	s_mov_b32 s51, 0
	v_or_b32_e32 v241, 1, v185
	v_or_b32_e32 v219, 2, v185
	v_or_b32_e32 v235, 3, v185
	v_add_u32_e32 v221, 0x80, v185
	v_add_u32_e32 v224, 0x81, v185
	v_add_u32_e32 v238, 0x82, v185
	v_add_u32_e32 v239, 0x83, v185
	v_cmp_gt_u32_e64 s[38:39], 3, v183
	v_cmp_lt_u32_e64 s[40:41], 12, v183
	v_add_u32_e32 v186, 3, v183
	s_waitcnt lgkmcnt(0)
	s_ashr_i32 s31, s10, 31
	s_ashr_i32 s78, s66, 31
	v_mov_b32_e32 v195, v3
	v_lshl_add_u32 v202, v17, 1, v2
	v_bfe_u32 v20, v202, 11, 4
	v_bfe_u32 v21, v202, 15, 2
	v_and_b32_e32 v202, 0xfffe07ff, v202
	v_lshl_or_b32 v202, v20, 13, v202
	v_lshl_or_b32 v202, v21, 11, v202
	v_mov_b32_e32 v203, v3
	v_add_u32_e32 v240, 0, v6
	s_mov_b64 s[56:57], s[0:1]
	s_mov_b64 s[58:59], s[44:45]
	s_barrier
	v_readlane_b32 s13, v254, 43
	v_readlane_b32 s14, v254, 44
	v_readlane_b32 s15, v254, 45
	v_readlane_b32 s16, v254, 46
	v_readlane_b32 s17, v254, 47
	v_readlane_b32 s18, v254, 48
	v_readlane_b32 s19, v254, 49
	v_readlane_b32 s22, v254, 52
	v_readlane_b32 s23, v254, 53
	v_readlane_b32 s26, v254, 56
	v_readlane_b32 s27, v254, 57
	s_branch .LBB0_420

.LBB0_451:
	s_and_b64 vcc, exec, s[0:1]
	s_cbranch_vccz .LBB0_419
	v_lshl_add_u32 v246, s61, 8, v201
	v_readlane_b32 s2, v252, 54
	v_readlane_b32 s3, v252, 55
	v_lshlrev_b32_e32 v247, 2, v246
	v_lshlrev_b32_e32 v246, 1, v246
	s_lshl_b32 s44, s60, 8
	s_cmpk_lg_i32 s60, 0x80
	s_cbranch_scc1 .Lg1c_nometa
	s_cmp_lg_u32 s11, 0
	s_cbranch_scc1 .Lg1c_nometa
	v_readlane_b32 s0, v255, 1
	v_readlane_b32 s1, v255, 2
	v_cmp_eq_u32_e64 s[16:17], 3, v183
	s_nop 1
	s_mov_b64 exec, s[16:17]
	v_cvt_pk_bf16_f32 v172, v120, v121
	v_cvt_pk_bf16_f32 v173, v122, v123
	v_cvt_pk_bf16_f32 v174, v116, v117
	v_cvt_pk_bf16_f32 v175, v118, v119
	global_store_dwordx4 v246, v[172:175], s[0:1]
	v_cvt_pk_bf16_f32 v212, v56, v57
	v_cvt_pk_bf16_f32 v213, v58, v59
	v_cvt_pk_bf16_f32 v214, v52, v53
	v_cvt_pk_bf16_f32 v215, v54, v55
	global_store_dwordx4 v246, v[212:215], s[0:1] offset:256
	s_add_u32 s0, s0, 0x1800
	s_addc_u32 s1, s1, 0
	v_cvt_pk_bf16_f32 v242, v112, v113
	v_cvt_pk_bf16_f32 v243, v114, v115
	v_cvt_pk_bf16_f32 v244, v108, v109
	v_cvt_pk_bf16_f32 v245, v110, v111
	global_store_dwordx4 v246, v[242:245], s[0:1]
	v_cvt_pk_bf16_f32 v204, v48, v49
	v_cvt_pk_bf16_f32 v205, v50, v51
	v_cvt_pk_bf16_f32 v206, v44, v45
	v_cvt_pk_bf16_f32 v207, v46, v47
	global_store_dwordx4 v246, v[204:207], s[0:1] offset:256
	s_add_u32 s0, s0, 0x1800
	s_addc_u32 s1, s1, 0
	v_cvt_pk_bf16_f32 v208, v104, v105
	v_cvt_pk_bf16_f32 v209, v106, v107
	v_cvt_pk_bf16_f32 v210, v100, v101
	v_cvt_pk_bf16_f32 v211, v102, v103
	global_store_dwordx4 v246, v[208:211], s[0:1]
	v_cvt_pk_bf16_f32 v172, v40, v41
	v_cvt_pk_bf16_f32 v173, v42, v43
	v_cvt_pk_bf16_f32 v174, v36, v37
	v_cvt_pk_bf16_f32 v175, v38, v39
	global_store_dwordx4 v246, v[172:175], s[0:1] offset:256
	s_mov_b64 exec, -1
.Lg1c_nometa:
	v_readlane_b32 s20, v254, 50
	v_readlane_b32 s21, v254, 51
	v_readlane_b32 s22, v254, 52
	v_readlane_b32 s23, v254, 53
	v_mul_u32_u24_e32 v198, 0x3400, v185
	v_add_u32_e32 v198, v198, v246
	v_cmp_eq_u32_e64 s[12:13], 0, v183
	v_cmp_eq_u32_e64 s[14:15], 15, v183
	s_add_u32 s24, s20, 0x3000
	s_addc_u32 s25, s21, 0
	s_add_u32 s26, s20, 0x6000
	s_addc_u32 s27, s21, 0
	s_add_u32 s18, s20, 0x9000
	s_addc_u32 s19, s21, 0
	s_add_u32 s4, s92, 0x4001000
	s_addc_u32 s5, s93, 0
	s_add_i32 s45, s44, s11
	s_lshr_b32 s45, s45, 6
	s_mul_i32 s46, s45, 6
	global_load_dwordx4 v[132:135], v247, s[22:23]
	global_load_dwordx4 v[136:139], v247, s[22:23] offset:16
	global_load_dwordx4 v[140:143], v247, s[20:21]
	global_load_dwordx4 v[144:147], v247, s[20:21] offset:16
	global_load_dwordx4 v[148:151], v247, s[24:25]
	global_load_dwordx4 v[152:155], v247, s[24:25] offset:16
	global_load_dwordx4 v[156:159], v247, s[26:27]
	global_load_dwordx4 v[160:163], v247, s[26:27] offset:16
	global_load_dwordx4 v[164:167], v247, s[18:19]
	global_load_dwordx4 v[168:171], v247, s[18:19] offset:16
	s_mov_b64 exec, s[12:13]
	s_add_i32 s0, s46, 3
	s_mulk_i32 s0, 0x1800
	s_add_u32 s0, s2, s0
	s_addc_u32 s1, s3, 0
	v_cvt_pk_bf16_f32 v172, v128, v129
	v_cvt_pk_bf16_f32 v173, v130, v131
	v_cvt_pk_bf16_f32 v174, v124, v125
	v_cvt_pk_bf16_f32 v175, v126, v127
	global_store_dwordx4 v246, v[172:175], s[0:1]
	v_cvt_pk_bf16_f32 v212, v64, v65
	v_cvt_pk_bf16_f32 v213, v66, v67
	v_cvt_pk_bf16_f32 v214, v60, v61
	v_cvt_pk_bf16_f32 v215, v62, v63
	global_store_dwordx4 v246, v[212:215], s[0:1] offset:256
	s_add_i32 s0, s46, 4
	s_mulk_i32 s0, 0x1800
	s_add_u32 s0, s2, s0
	s_addc_u32 s1, s3, 0
	v_cvt_pk_bf16_f32 v242, v120, v121
	v_cvt_pk_bf16_f32 v243, v122, v123
	v_cvt_pk_bf16_f32 v244, v116, v117
	v_cvt_pk_bf16_f32 v245, v118, v119
	global_store_dwordx4 v246, v[242:245], s[0:1]
	v_cvt_pk_bf16_f32 v204, v56, v57
	v_cvt_pk_bf16_f32 v205, v58, v59
	v_cvt_pk_bf16_f32 v206, v52, v53
	v_cvt_pk_bf16_f32 v207, v54, v55
	global_store_dwordx4 v246, v[204:207], s[0:1] offset:256
	s_add_i32 s0, s46, 5
	s_mulk_i32 s0, 0x1800
	s_add_u32 s0, s2, s0
	s_addc_u32 s1, s3, 0
	v_cvt_pk_bf16_f32 v208, v112, v113
	v_cvt_pk_bf16_f32 v209, v114, v115
	v_cvt_pk_bf16_f32 v210, v108, v109
	v_cvt_pk_bf16_f32 v211, v110, v111
	global_store_dwordx4 v246, v[208:211], s[0:1]
	v_cvt_pk_bf16_f32 v172, v48, v49
	v_cvt_pk_bf16_f32 v173, v50, v51
	v_cvt_pk_bf16_f32 v174, v44, v45
	v_cvt_pk_bf16_f32 v175, v46, v47
	global_store_dwordx4 v246, v[172:175], s[0:1] offset:256
	s_mov_b64 exec, s[14:15]
	s_add_i32 s0, s46, 0
	s_mulk_i32 s0, 0x1800
	s_add_u32 s0, s2, s0
	s_addc_u32 s1, s3, 0
	v_cvt_pk_bf16_f32 v212, v120, v121
	v_cvt_pk_bf16_f32 v213, v122, v123
	v_cvt_pk_bf16_f32 v214, v116, v117
	v_cvt_pk_bf16_f32 v215, v118, v119
	global_store_dwordx4 v246, v[212:215], s[0:1]
	v_cvt_pk_bf16_f32 v242, v56, v57
	v_cvt_pk_bf16_f32 v243, v58, v59
	v_cvt_pk_bf16_f32 v244, v52, v53
	v_cvt_pk_bf16_f32 v245, v54, v55
	global_store_dwordx4 v246, v[242:245], s[0:1] offset:256
	s_add_i32 s0, s46, 1
	s_mulk_i32 s0, 0x1800
	s_add_u32 s0, s2, s0
	s_addc_u32 s1, s3, 0
	v_cvt_pk_bf16_f32 v204, v112, v113
	v_cvt_pk_bf16_f32 v205, v114, v115
	v_cvt_pk_bf16_f32 v206, v108, v109
	v_cvt_pk_bf16_f32 v207, v110, v111
	global_store_dwordx4 v246, v[204:207], s[0:1]
	v_cvt_pk_bf16_f32 v208, v48, v49
	v_cvt_pk_bf16_f32 v209, v50, v51
	v_cvt_pk_bf16_f32 v210, v44, v45
	v_cvt_pk_bf16_f32 v211, v46, v47
	global_store_dwordx4 v246, v[208:211], s[0:1] offset:256
	s_add_i32 s0, s46, 2
	s_mulk_i32 s0, 0x1800
	s_add_u32 s0, s2, s0
	s_addc_u32 s1, s3, 0
	v_cvt_pk_bf16_f32 v172, v104, v105
	v_cvt_pk_bf16_f32 v173, v106, v107
	v_cvt_pk_bf16_f32 v174, v100, v101
	v_cvt_pk_bf16_f32 v175, v102, v103
	global_store_dwordx4 v246, v[172:175], s[0:1]
	v_cvt_pk_bf16_f32 v212, v40, v41
	v_cvt_pk_bf16_f32 v213, v42, v43
	v_cvt_pk_bf16_f32 v214, v36, v37
	v_cvt_pk_bf16_f32 v215, v38, v39
	global_store_dwordx4 v246, v[212:215], s[0:1] offset:256
	s_mov_b64 exec, s[12:13]
	s_add_i32 s0, s46, 15
	s_mulk_i32 s0, 0x1800
	s_add_u32 s0, s2, s0
	s_addc_u32 s1, s3, 0
	v_cvt_pk_bf16_f32 v242, v96, v97
	v_cvt_pk_bf16_f32 v243, v98, v99
	v_cvt_pk_bf16_f32 v244, v92, v93
	v_cvt_pk_bf16_f32 v245, v94, v95
	global_store_dwordx4 v246, v[242:245], s[0:1]
	v_cvt_pk_bf16_f32 v204, v32, v33
	v_cvt_pk_bf16_f32 v205, v34, v35
	v_cvt_pk_bf16_f32 v206, v28, v29
	v_cvt_pk_bf16_f32 v207, v30, v31
	global_store_dwordx4 v246, v[204:207], s[0:1] offset:256
	s_add_i32 s0, s46, 16
	s_mulk_i32 s0, 0x1800
	s_add_u32 s0, s2, s0
	s_addc_u32 s1, s3, 0
	v_cvt_pk_bf16_f32 v208, v88, v89
	v_cvt_pk_bf16_f32 v209, v90, v91
	v_cvt_pk_bf16_f32 v210, v84, v85
	v_cvt_pk_bf16_f32 v211, v86, v87
	global_store_dwordx4 v246, v[208:211], s[0:1]
	v_cvt_pk_bf16_f32 v172, v24, v25
	v_cvt_pk_bf16_f32 v173, v26, v27
	v_cvt_pk_bf16_f32 v174, v20, v21
	v_cvt_pk_bf16_f32 v175, v22, v23
	global_store_dwordx4 v246, v[172:175], s[0:1] offset:256
	s_add_i32 s0, s46, 17
	s_mulk_i32 s0, 0x1800
	s_add_u32 s0, s2, s0
	s_addc_u32 s1, s3, 0
	v_cvt_pk_bf16_f32 v212, v80, v81
	v_cvt_pk_bf16_f32 v213, v82, v83
	v_cvt_pk_bf16_f32 v214, v76, v77
	v_cvt_pk_bf16_f32 v215, v78, v79
	global_store_dwordx4 v246, v[212:215], s[0:1]
	v_cvt_pk_bf16_f32 v242, v16, v17
	v_cvt_pk_bf16_f32 v243, v18, v19
	v_cvt_pk_bf16_f32 v244, v12, v13
	v_cvt_pk_bf16_f32 v245, v14, v15
	global_store_dwordx4 v246, v[242:245], s[0:1] offset:256
	s_mov_b64 exec, s[14:15]
	s_add_i32 s0, s46, 12
	s_mulk_i32 s0, 0x1800
	s_add_u32 s0, s2, s0
	s_addc_u32 s1, s3, 0
	v_cvt_pk_bf16_f32 v204, v88, v89
	v_cvt_pk_bf16_f32 v205, v90, v91
	v_cvt_pk_bf16_f32 v206, v84, v85
	v_cvt_pk_bf16_f32 v207, v86, v87
	global_store_dwordx4 v246, v[204:207], s[0:1]
	v_cvt_pk_bf16_f32 v208, v24, v25
	v_cvt_pk_bf16_f32 v209, v26, v27
	v_cvt_pk_bf16_f32 v210, v20, v21
	v_cvt_pk_bf16_f32 v211, v22, v23
	global_store_dwordx4 v246, v[208:211], s[0:1] offset:256
	s_add_i32 s0, s46, 13
	s_mulk_i32 s0, 0x1800
	s_add_u32 s0, s2, s0
	s_addc_u32 s1, s3, 0
	v_cvt_pk_bf16_f32 v172, v80, v81
	v_cvt_pk_bf16_f32 v173, v82, v83
	v_cvt_pk_bf16_f32 v174, v76, v77
	v_cvt_pk_bf16_f32 v175, v78, v79
	global_store_dwordx4 v246, v[172:175], s[0:1]
	v_cvt_pk_bf16_f32 v212, v16, v17
	v_cvt_pk_bf16_f32 v213, v18, v19
	v_cvt_pk_bf16_f32 v214, v12, v13
	v_cvt_pk_bf16_f32 v215, v14, v15
	global_store_dwordx4 v246, v[212:215], s[0:1] offset:256
	s_add_i32 s0, s46, 14
	s_mulk_i32 s0, 0x1800
	s_add_u32 s0, s2, s0
	s_addc_u32 s1, s3, 0
	v_cvt_pk_bf16_f32 v242, v72, v73
	v_cvt_pk_bf16_f32 v243, v74, v75
	v_cvt_pk_bf16_f32 v244, v68, v69
	v_cvt_pk_bf16_f32 v245, v70, v71
	global_store_dwordx4 v246, v[242:245], s[0:1]
	v_cvt_pk_bf16_f32 v204, v8, v9
	v_cvt_pk_bf16_f32 v205, v10, v11
	v_cvt_pk_bf16_f32 v206, v4, v5
	v_cvt_pk_bf16_f32 v207, v6, v7
	global_store_dwordx4 v246, v[204:207], s[0:1] offset:256
	s_mov_b64 exec, -1
	s_mov_b32 s16, 0xbfb8aa3b
	s_mov_b32 s17, 0xbfb8aa3b
	s_waitcnt vmcnt(24)
	v_mov_b32_dpp v172, v104 row_shr:1 row_mask:0xf bank_mask:0xf bound_ctrl:1
	v_mov_b32_dpp v173, v105 row_shr:1 row_mask:0xf bank_mask:0xf bound_ctrl:1
	v_mov_b32_dpp v174, v112 row_shr:1 row_mask:0xf bank_mask:0xf bound_ctrl:1
	v_mov_b32_dpp v175, v113 row_shr:1 row_mask:0xf bank_mask:0xf bound_ctrl:1
	v_mov_b32_dpp v212, v120 row_shr:1 row_mask:0xf bank_mask:0xf bound_ctrl:1
	v_mov_b32_dpp v213, v121 row_shr:1 row_mask:0xf bank_mask:0xf bound_ctrl:1
	v_pk_fma_f32 v[104:105], v[104:105], v[164:165], v[132:133]
	v_pk_fma_f32 v[104:105], v[112:113], v[156:157], v[104:105]
	v_pk_fma_f32 v[104:105], v[120:121], v[148:149], v[104:105]
	v_pk_fma_f32 v[104:105], v[128:129], v[140:141], v[104:105]
	v_pk_fma_f32 v[112:113], v[112:113], v[164:165], v[132:133]
	v_pk_fma_f32 v[112:113], v[120:121], v[156:157], v[112:113]
	v_pk_fma_f32 v[112:113], v[128:129], v[148:149], v[112:113]
	v_pk_fma_f32 v[112:113], v[172:173], v[140:141], v[112:113]
	v_pk_fma_f32 v[120:121], v[120:121], v[164:165], v[132:133]
	v_pk_fma_f32 v[120:121], v[128:129], v[156:157], v[120:121]
	v_pk_fma_f32 v[120:121], v[172:173], v[148:149], v[120:121]
	v_pk_fma_f32 v[120:121], v[174:175], v[140:141], v[120:121]
	v_pk_fma_f32 v[128:129], v[128:129], v[164:165], v[132:133]
	v_pk_fma_f32 v[128:129], v[172:173], v[156:157], v[128:129]
	v_pk_fma_f32 v[128:129], v[174:175], v[148:149], v[128:129]
	v_pk_fma_f32 v[128:129], v[212:213], v[140:141], v[128:129]
	v_pk_mul_f32 v[214:215], v[128:129], s[16:17]
	v_pk_mul_f32 v[242:243], v[120:121], s[16:17]
	v_pk_mul_f32 v[244:245], v[112:113], s[16:17]
	v_pk_mul_f32 v[246:247], v[104:105], s[16:17]
	v_exp_f32_e32 v214, v214
	v_exp_f32_e32 v215, v215
	v_exp_f32_e32 v242, v242
	v_exp_f32_e32 v243, v243
	v_exp_f32_e32 v244, v244
	v_exp_f32_e32 v245, v245
	v_exp_f32_e32 v246, v246
	v_exp_f32_e32 v247, v247
	v_pk_add_f32 v[214:215], v[214:215], 1.0 op_sel_hi:[1,0]
	v_pk_add_f32 v[242:243], v[242:243], 1.0 op_sel_hi:[1,0]
	v_pk_add_f32 v[244:245], v[244:245], 1.0 op_sel_hi:[1,0]
	v_pk_add_f32 v[246:247], v[246:247], 1.0 op_sel_hi:[1,0]
	v_rcp_f32_e32 v214, v214
	v_rcp_f32_e32 v215, v215
	v_rcp_f32_e32 v242, v242
	v_rcp_f32_e32 v243, v243
	v_rcp_f32_e32 v244, v244
	v_rcp_f32_e32 v245, v245
	v_rcp_f32_e32 v246, v246
	v_rcp_f32_e32 v247, v247
	v_pk_mul_f32 v[128:129], v[128:129], v[214:215]
	v_pk_mul_f32 v[120:121], v[120:121], v[242:243]
	v_pk_mul_f32 v[112:113], v[112:113], v[244:245]
	v_pk_mul_f32 v[104:105], v[104:105], v[246:247]
	v_cvt_pk_bf16_f32 v128, v128, v129
	v_cvt_pk_bf16_f32 v120, v120, v121
	v_cvt_pk_bf16_f32 v112, v112, v113
	v_cvt_pk_bf16_f32 v104, v104, v105
	v_mov_b32_dpp v172, v106 row_shr:1 row_mask:0xf bank_mask:0xf bound_ctrl:1
	v_mov_b32_dpp v173, v107 row_shr:1 row_mask:0xf bank_mask:0xf bound_ctrl:1
	v_mov_b32_dpp v174, v114 row_shr:1 row_mask:0xf bank_mask:0xf bound_ctrl:1
	v_mov_b32_dpp v175, v115 row_shr:1 row_mask:0xf bank_mask:0xf bound_ctrl:1
	v_mov_b32_dpp v212, v122 row_shr:1 row_mask:0xf bank_mask:0xf bound_ctrl:1
	v_mov_b32_dpp v213, v123 row_shr:1 row_mask:0xf bank_mask:0xf bound_ctrl:1
	v_pk_fma_f32 v[106:107], v[106:107], v[166:167], v[134:135]
	v_pk_fma_f32 v[106:107], v[114:115], v[158:159], v[106:107]
	v_pk_fma_f32 v[106:107], v[122:123], v[150:151], v[106:107]
	v_pk_fma_f32 v[106:107], v[130:131], v[142:143], v[106:107]
	v_pk_fma_f32 v[114:115], v[114:115], v[166:167], v[134:135]
	v_pk_fma_f32 v[114:115], v[122:123], v[158:159], v[114:115]
	v_pk_fma_f32 v[114:115], v[130:131], v[150:151], v[114:115]
	v_pk_fma_f32 v[114:115], v[172:173], v[142:143], v[114:115]
	v_pk_fma_f32 v[122:123], v[122:123], v[166:167], v[134:135]
	v_pk_fma_f32 v[122:123], v[130:131], v[158:159], v[122:123]
	v_pk_fma_f32 v[122:123], v[172:173], v[150:151], v[122:123]
	v_pk_fma_f32 v[122:123], v[174:175], v[142:143], v[122:123]
	v_pk_fma_f32 v[130:131], v[130:131], v[166:167], v[134:135]
	v_pk_fma_f32 v[130:131], v[172:173], v[158:159], v[130:131]
	v_pk_fma_f32 v[130:131], v[174:175], v[150:151], v[130:131]
	v_pk_fma_f32 v[130:131], v[212:213], v[142:143], v[130:131]
	v_pk_mul_f32 v[214:215], v[130:131], s[16:17]
	v_pk_mul_f32 v[242:243], v[122:123], s[16:17]
	v_pk_mul_f32 v[244:245], v[114:115], s[16:17]
	v_pk_mul_f32 v[246:247], v[106:107], s[16:17]
	v_exp_f32_e32 v214, v214
	v_exp_f32_e32 v215, v215
	v_exp_f32_e32 v242, v242
	v_exp_f32_e32 v243, v243
	v_exp_f32_e32 v244, v244
	v_exp_f32_e32 v245, v245
	v_exp_f32_e32 v246, v246
	v_exp_f32_e32 v247, v247
	v_pk_add_f32 v[214:215], v[214:215], 1.0 op_sel_hi:[1,0]
	v_pk_add_f32 v[242:243], v[242:243], 1.0 op_sel_hi:[1,0]
	v_pk_add_f32 v[244:245], v[244:245], 1.0 op_sel_hi:[1,0]
	v_pk_add_f32 v[246:247], v[246:247], 1.0 op_sel_hi:[1,0]
	v_rcp_f32_e32 v214, v214
	v_rcp_f32_e32 v215, v215
	v_rcp_f32_e32 v242, v242
	v_rcp_f32_e32 v243, v243
	v_rcp_f32_e32 v244, v244
	v_rcp_f32_e32 v245, v245
	v_rcp_f32_e32 v246, v246
	v_rcp_f32_e32 v247, v247
	v_pk_mul_f32 v[130:131], v[130:131], v[214:215]
	v_pk_mul_f32 v[122:123], v[122:123], v[242:243]
	v_pk_mul_f32 v[114:115], v[114:115], v[244:245]
	v_pk_mul_f32 v[106:107], v[106:107], v[246:247]
	v_cvt_pk_bf16_f32 v129, v130, v131
	v_cvt_pk_bf16_f32 v121, v122, v123
	v_cvt_pk_bf16_f32 v113, v114, v115
	v_cvt_pk_bf16_f32 v105, v106, v107
	v_mov_b32_dpp v172, v100 row_shr:1 row_mask:0xf bank_mask:0xf bound_ctrl:1
	v_mov_b32_dpp v173, v101 row_shr:1 row_mask:0xf bank_mask:0xf bound_ctrl:1
	v_mov_b32_dpp v174, v108 row_shr:1 row_mask:0xf bank_mask:0xf bound_ctrl:1
	v_mov_b32_dpp v175, v109 row_shr:1 row_mask:0xf bank_mask:0xf bound_ctrl:1
	v_mov_b32_dpp v212, v116 row_shr:1 row_mask:0xf bank_mask:0xf bound_ctrl:1
	v_mov_b32_dpp v213, v117 row_shr:1 row_mask:0xf bank_mask:0xf bound_ctrl:1
	v_pk_fma_f32 v[100:101], v[100:101], v[168:169], v[136:137]
	v_pk_fma_f32 v[100:101], v[108:109], v[160:161], v[100:101]
	v_pk_fma_f32 v[100:101], v[116:117], v[152:153], v[100:101]
	v_pk_fma_f32 v[100:101], v[124:125], v[144:145], v[100:101]
	v_pk_fma_f32 v[108:109], v[108:109], v[168:169], v[136:137]
	v_pk_fma_f32 v[108:109], v[116:117], v[160:161], v[108:109]
	v_pk_fma_f32 v[108:109], v[124:125], v[152:153], v[108:109]
	v_pk_fma_f32 v[108:109], v[172:173], v[144:145], v[108:109]
	v_pk_fma_f32 v[116:117], v[116:117], v[168:169], v[136:137]
	v_pk_fma_f32 v[116:117], v[124:125], v[160:161], v[116:117]
	v_pk_fma_f32 v[116:117], v[172:173], v[152:153], v[116:117]
	v_pk_fma_f32 v[116:117], v[174:175], v[144:145], v[116:117]
	v_pk_fma_f32 v[124:125], v[124:125], v[168:169], v[136:137]
	v_pk_fma_f32 v[124:125], v[172:173], v[160:161], v[124:125]
	v_pk_fma_f32 v[124:125], v[174:175], v[152:153], v[124:125]
	v_pk_fma_f32 v[124:125], v[212:213], v[144:145], v[124:125]
	v_pk_mul_f32 v[214:215], v[124:125], s[16:17]
	v_pk_mul_f32 v[242:243], v[116:117], s[16:17]
	v_pk_mul_f32 v[244:245], v[108:109], s[16:17]
	v_pk_mul_f32 v[246:247], v[100:101], s[16:17]
	v_exp_f32_e32 v214, v214
	v_exp_f32_e32 v215, v215
	v_exp_f32_e32 v242, v242
	v_exp_f32_e32 v243, v243
	v_exp_f32_e32 v244, v244
	v_exp_f32_e32 v245, v245
	v_exp_f32_e32 v246, v246
	v_exp_f32_e32 v247, v247
	v_pk_add_f32 v[214:215], v[214:215], 1.0 op_sel_hi:[1,0]
	v_pk_add_f32 v[242:243], v[242:243], 1.0 op_sel_hi:[1,0]
	v_pk_add_f32 v[244:245], v[244:245], 1.0 op_sel_hi:[1,0]
	v_pk_add_f32 v[246:247], v[246:247], 1.0 op_sel_hi:[1,0]
	v_rcp_f32_e32 v214, v214
	v_rcp_f32_e32 v215, v215
	v_rcp_f32_e32 v242, v242
	v_rcp_f32_e32 v243, v243
	v_rcp_f32_e32 v244, v244
	v_rcp_f32_e32 v245, v245
	v_rcp_f32_e32 v246, v246
	v_rcp_f32_e32 v247, v247
	v_pk_mul_f32 v[124:125], v[124:125], v[214:215]
	v_pk_mul_f32 v[116:117], v[116:117], v[242:243]
	v_pk_mul_f32 v[108:109], v[108:109], v[244:245]
	v_pk_mul_f32 v[100:101], v[100:101], v[246:247]
	v_cvt_pk_bf16_f32 v130, v124, v125
	v_cvt_pk_bf16_f32 v122, v116, v117
	v_cvt_pk_bf16_f32 v114, v108, v109
	v_cvt_pk_bf16_f32 v106, v100, v101
	v_mov_b32_dpp v172, v102 row_shr:1 row_mask:0xf bank_mask:0xf bound_ctrl:1
	v_mov_b32_dpp v173, v103 row_shr:1 row_mask:0xf bank_mask:0xf bound_ctrl:1
	v_mov_b32_dpp v174, v110 row_shr:1 row_mask:0xf bank_mask:0xf bound_ctrl:1
	v_mov_b32_dpp v175, v111 row_shr:1 row_mask:0xf bank_mask:0xf bound_ctrl:1
	v_mov_b32_dpp v212, v118 row_shr:1 row_mask:0xf bank_mask:0xf bound_ctrl:1
	v_mov_b32_dpp v213, v119 row_shr:1 row_mask:0xf bank_mask:0xf bound_ctrl:1
	v_pk_fma_f32 v[102:103], v[102:103], v[170:171], v[138:139]
	v_pk_fma_f32 v[102:103], v[110:111], v[162:163], v[102:103]
	v_pk_fma_f32 v[102:103], v[118:119], v[154:155], v[102:103]
	v_pk_fma_f32 v[102:103], v[126:127], v[146:147], v[102:103]
	v_pk_fma_f32 v[110:111], v[110:111], v[170:171], v[138:139]
	v_pk_fma_f32 v[110:111], v[118:119], v[162:163], v[110:111]
	v_pk_fma_f32 v[110:111], v[126:127], v[154:155], v[110:111]
	v_pk_fma_f32 v[110:111], v[172:173], v[146:147], v[110:111]
	v_pk_fma_f32 v[118:119], v[118:119], v[170:171], v[138:139]
	v_pk_fma_f32 v[118:119], v[126:127], v[162:163], v[118:119]
	v_pk_fma_f32 v[118:119], v[172:173], v[154:155], v[118:119]
	v_pk_fma_f32 v[118:119], v[174:175], v[146:147], v[118:119]
	v_pk_fma_f32 v[126:127], v[126:127], v[170:171], v[138:139]
	v_pk_fma_f32 v[126:127], v[172:173], v[162:163], v[126:127]
	v_pk_fma_f32 v[126:127], v[174:175], v[154:155], v[126:127]
	v_pk_fma_f32 v[126:127], v[212:213], v[146:147], v[126:127]
	v_pk_mul_f32 v[214:215], v[126:127], s[16:17]
	v_pk_mul_f32 v[242:243], v[118:119], s[16:17]
	v_pk_mul_f32 v[244:245], v[110:111], s[16:17]
	v_pk_mul_f32 v[246:247], v[102:103], s[16:17]
	v_exp_f32_e32 v214, v214
	v_exp_f32_e32 v215, v215
	v_exp_f32_e32 v242, v242
	v_exp_f32_e32 v243, v243
	v_exp_f32_e32 v244, v244
	v_exp_f32_e32 v245, v245
	v_exp_f32_e32 v246, v246
	v_exp_f32_e32 v247, v247
	v_pk_add_f32 v[214:215], v[214:215], 1.0 op_sel_hi:[1,0]
	v_pk_add_f32 v[242:243], v[242:243], 1.0 op_sel_hi:[1,0]
	v_pk_add_f32 v[244:245], v[244:245], 1.0 op_sel_hi:[1,0]
	v_pk_add_f32 v[246:247], v[246:247], 1.0 op_sel_hi:[1,0]
	v_rcp_f32_e32 v214, v214
	v_rcp_f32_e32 v215, v215
	v_rcp_f32_e32 v242, v242
	v_rcp_f32_e32 v243, v243
	v_rcp_f32_e32 v244, v244
	v_rcp_f32_e32 v245, v245
	v_rcp_f32_e32 v246, v246
	v_rcp_f32_e32 v247, v247
	v_pk_mul_f32 v[126:127], v[126:127], v[214:215]
	v_pk_mul_f32 v[118:119], v[118:119], v[242:243]
	v_pk_mul_f32 v[110:111], v[110:111], v[244:245]
	v_pk_mul_f32 v[102:103], v[102:103], v[246:247]
	v_cvt_pk_bf16_f32 v131, v126, v127
	v_cvt_pk_bf16_f32 v123, v118, v119
	v_cvt_pk_bf16_f32 v115, v110, v111
	v_cvt_pk_bf16_f32 v107, v102, v103
	s_add_i32 s0, s44, 0
	s_mul_i32 s0, s0, s29
	s_add_u32 s0, s4, s0
	s_addc_u32 s1, s5, 0
	global_store_dwordx4 v198, v[128:131], s[0:1]
	s_add_i32 s0, s44, 1
	s_mul_i32 s0, s0, s29
	s_add_u32 s0, s4, s0
	s_addc_u32 s1, s5, 0
	global_store_dwordx4 v198, v[120:123], s[0:1]
	s_add_i32 s0, s44, 2
	s_mul_i32 s0, s0, s29
	s_add_u32 s0, s4, s0
	s_addc_u32 s1, s5, 0
	global_store_dwordx4 v198, v[112:115], s[0:1]
	s_add_i32 s0, s44, 3
	s_mul_i32 s0, s0, s29
	s_add_u32 s0, s4, s0
	s_addc_u32 s1, s5, 0
	global_store_dwordx4 v198, v[104:107], s[0:1]
	v_lshl_add_u32 v172, s61, 8, v201
	v_lshlrev_b32_e32 v172, 2, v172
	global_load_dwordx4 v[128:131], v172, s[22:23] offset:512
	global_load_dwordx4 v[124:127], v172, s[22:23] offset:528
	global_load_dwordx4 v[120:123], v172, s[20:21] offset:512
	global_load_dwordx4 v[116:119], v172, s[20:21] offset:528
	global_load_dwordx4 v[112:115], v172, s[24:25] offset:512
	global_load_dwordx4 v[108:111], v172, s[24:25] offset:528
	global_load_dwordx4 v[104:107], v172, s[26:27] offset:512
	global_load_dwordx4 v[100:103], v172, s[26:27] offset:528
	global_load_dwordx4 v[204:207], v172, s[18:19] offset:512
	global_load_dwordx4 v[208:211], v172, s[18:19] offset:528
	v_mov_b32_dpp v172, v72 row_shr:1 row_mask:0xf bank_mask:0xf bound_ctrl:1
	v_mov_b32_dpp v173, v73 row_shr:1 row_mask:0xf bank_mask:0xf bound_ctrl:1
	v_mov_b32_dpp v174, v80 row_shr:1 row_mask:0xf bank_mask:0xf bound_ctrl:1
	v_mov_b32_dpp v175, v81 row_shr:1 row_mask:0xf bank_mask:0xf bound_ctrl:1
	v_mov_b32_dpp v212, v88 row_shr:1 row_mask:0xf bank_mask:0xf bound_ctrl:1
	v_mov_b32_dpp v213, v89 row_shr:1 row_mask:0xf bank_mask:0xf bound_ctrl:1
	v_pk_fma_f32 v[72:73], v[72:73], v[164:165], v[132:133]
	v_pk_fma_f32 v[72:73], v[80:81], v[156:157], v[72:73]
	v_pk_fma_f32 v[72:73], v[88:89], v[148:149], v[72:73]
	v_pk_fma_f32 v[72:73], v[96:97], v[140:141], v[72:73]
	v_pk_fma_f32 v[80:81], v[80:81], v[164:165], v[132:133]
	v_pk_fma_f32 v[80:81], v[88:89], v[156:157], v[80:81]
	v_pk_fma_f32 v[80:81], v[96:97], v[148:149], v[80:81]
	v_pk_fma_f32 v[80:81], v[172:173], v[140:141], v[80:81]
	v_pk_fma_f32 v[88:89], v[88:89], v[164:165], v[132:133]
	v_pk_fma_f32 v[88:89], v[96:97], v[156:157], v[88:89]
	v_pk_fma_f32 v[88:89], v[172:173], v[148:149], v[88:89]
	v_pk_fma_f32 v[88:89], v[174:175], v[140:141], v[88:89]
	v_pk_fma_f32 v[96:97], v[96:97], v[164:165], v[132:133]
	v_pk_fma_f32 v[96:97], v[172:173], v[156:157], v[96:97]
	v_pk_fma_f32 v[96:97], v[174:175], v[148:149], v[96:97]
	v_pk_fma_f32 v[96:97], v[212:213], v[140:141], v[96:97]
	v_pk_mul_f32 v[214:215], v[96:97], s[16:17]
	v_pk_mul_f32 v[242:243], v[88:89], s[16:17]
	v_pk_mul_f32 v[244:245], v[80:81], s[16:17]
	v_pk_mul_f32 v[246:247], v[72:73], s[16:17]
	v_exp_f32_e32 v214, v214
	v_exp_f32_e32 v215, v215
	v_exp_f32_e32 v242, v242
	v_exp_f32_e32 v243, v243
	v_exp_f32_e32 v244, v244
	v_exp_f32_e32 v245, v245
	v_exp_f32_e32 v246, v246
	v_exp_f32_e32 v247, v247
	v_pk_add_f32 v[214:215], v[214:215], 1.0 op_sel_hi:[1,0]
	v_pk_add_f32 v[242:243], v[242:243], 1.0 op_sel_hi:[1,0]
	v_pk_add_f32 v[244:245], v[244:245], 1.0 op_sel_hi:[1,0]
	v_pk_add_f32 v[246:247], v[246:247], 1.0 op_sel_hi:[1,0]
	v_rcp_f32_e32 v214, v214
	v_rcp_f32_e32 v215, v215
	v_rcp_f32_e32 v242, v242
	v_rcp_f32_e32 v243, v243
	v_rcp_f32_e32 v244, v244
	v_rcp_f32_e32 v245, v245
	v_rcp_f32_e32 v246, v246
	v_rcp_f32_e32 v247, v247
	v_pk_mul_f32 v[96:97], v[96:97], v[214:215]
	v_pk_mul_f32 v[88:89], v[88:89], v[242:243]
	v_pk_mul_f32 v[80:81], v[80:81], v[244:245]
	v_pk_mul_f32 v[72:73], v[72:73], v[246:247]
	v_cvt_pk_bf16_f32 v96, v96, v97
	v_cvt_pk_bf16_f32 v88, v88, v89
	v_cvt_pk_bf16_f32 v80, v80, v81
	v_cvt_pk_bf16_f32 v72, v72, v73
	v_mov_b32_dpp v172, v74 row_shr:1 row_mask:0xf bank_mask:0xf bound_ctrl:1
	v_mov_b32_dpp v173, v75 row_shr:1 row_mask:0xf bank_mask:0xf bound_ctrl:1
	v_mov_b32_dpp v174, v82 row_shr:1 row_mask:0xf bank_mask:0xf bound_ctrl:1
	v_mov_b32_dpp v175, v83 row_shr:1 row_mask:0xf bank_mask:0xf bound_ctrl:1
	v_mov_b32_dpp v212, v90 row_shr:1 row_mask:0xf bank_mask:0xf bound_ctrl:1
	v_mov_b32_dpp v213, v91 row_shr:1 row_mask:0xf bank_mask:0xf bound_ctrl:1
	v_pk_fma_f32 v[74:75], v[74:75], v[166:167], v[134:135]
	v_pk_fma_f32 v[74:75], v[82:83], v[158:159], v[74:75]
	v_pk_fma_f32 v[74:75], v[90:91], v[150:151], v[74:75]
	v_pk_fma_f32 v[74:75], v[98:99], v[142:143], v[74:75]
	v_pk_fma_f32 v[82:83], v[82:83], v[166:167], v[134:135]
	v_pk_fma_f32 v[82:83], v[90:91], v[158:159], v[82:83]
	v_pk_fma_f32 v[82:83], v[98:99], v[150:151], v[82:83]
	v_pk_fma_f32 v[82:83], v[172:173], v[142:143], v[82:83]
	v_pk_fma_f32 v[90:91], v[90:91], v[166:167], v[134:135]
	v_pk_fma_f32 v[90:91], v[98:99], v[158:159], v[90:91]
	v_pk_fma_f32 v[90:91], v[172:173], v[150:151], v[90:91]
	v_pk_fma_f32 v[90:91], v[174:175], v[142:143], v[90:91]
	v_pk_fma_f32 v[98:99], v[98:99], v[166:167], v[134:135]
	v_pk_fma_f32 v[98:99], v[172:173], v[158:159], v[98:99]
	v_pk_fma_f32 v[98:99], v[174:175], v[150:151], v[98:99]
	v_pk_fma_f32 v[98:99], v[212:213], v[142:143], v[98:99]
	v_pk_mul_f32 v[214:215], v[98:99], s[16:17]
	v_pk_mul_f32 v[242:243], v[90:91], s[16:17]
	v_pk_mul_f32 v[244:245], v[82:83], s[16:17]
	v_pk_mul_f32 v[246:247], v[74:75], s[16:17]
	v_exp_f32_e32 v214, v214
	v_exp_f32_e32 v215, v215
	v_exp_f32_e32 v242, v242
	v_exp_f32_e32 v243, v243
	v_exp_f32_e32 v244, v244
	v_exp_f32_e32 v245, v245
	v_exp_f32_e32 v246, v246
	v_exp_f32_e32 v247, v247
	v_pk_add_f32 v[214:215], v[214:215], 1.0 op_sel_hi:[1,0]
	v_pk_add_f32 v[242:243], v[242:243], 1.0 op_sel_hi:[1,0]
	v_pk_add_f32 v[244:245], v[244:245], 1.0 op_sel_hi:[1,0]
	v_pk_add_f32 v[246:247], v[246:247], 1.0 op_sel_hi:[1,0]
	v_rcp_f32_e32 v214, v214
	v_rcp_f32_e32 v215, v215
	v_rcp_f32_e32 v242, v242
	v_rcp_f32_e32 v243, v243
	v_rcp_f32_e32 v244, v244
	v_rcp_f32_e32 v245, v245
	v_rcp_f32_e32 v246, v246
	v_rcp_f32_e32 v247, v247
	v_pk_mul_f32 v[98:99], v[98:99], v[214:215]
	v_pk_mul_f32 v[90:91], v[90:91], v[242:243]
	v_pk_mul_f32 v[82:83], v[82:83], v[244:245]
	v_pk_mul_f32 v[74:75], v[74:75], v[246:247]
	v_cvt_pk_bf16_f32 v97, v98, v99
	v_cvt_pk_bf16_f32 v89, v90, v91
	v_cvt_pk_bf16_f32 v81, v82, v83
	v_cvt_pk_bf16_f32 v73, v74, v75
	v_mov_b32_dpp v172, v68 row_shr:1 row_mask:0xf bank_mask:0xf bound_ctrl:1
	v_mov_b32_dpp v173, v69 row_shr:1 row_mask:0xf bank_mask:0xf bound_ctrl:1
	v_mov_b32_dpp v174, v76 row_shr:1 row_mask:0xf bank_mask:0xf bound_ctrl:1
	v_mov_b32_dpp v175, v77 row_shr:1 row_mask:0xf bank_mask:0xf bound_ctrl:1
	v_mov_b32_dpp v212, v84 row_shr:1 row_mask:0xf bank_mask:0xf bound_ctrl:1
	v_mov_b32_dpp v213, v85 row_shr:1 row_mask:0xf bank_mask:0xf bound_ctrl:1
	v_pk_fma_f32 v[68:69], v[68:69], v[168:169], v[136:137]
	v_pk_fma_f32 v[68:69], v[76:77], v[160:161], v[68:69]
	v_pk_fma_f32 v[68:69], v[84:85], v[152:153], v[68:69]
	v_pk_fma_f32 v[68:69], v[92:93], v[144:145], v[68:69]
	v_pk_fma_f32 v[76:77], v[76:77], v[168:169], v[136:137]
	v_pk_fma_f32 v[76:77], v[84:85], v[160:161], v[76:77]
	v_pk_fma_f32 v[76:77], v[92:93], v[152:153], v[76:77]
	v_pk_fma_f32 v[76:77], v[172:173], v[144:145], v[76:77]
	v_pk_fma_f32 v[84:85], v[84:85], v[168:169], v[136:137]
	v_pk_fma_f32 v[84:85], v[92:93], v[160:161], v[84:85]
	v_pk_fma_f32 v[84:85], v[172:173], v[152:153], v[84:85]
	v_pk_fma_f32 v[84:85], v[174:175], v[144:145], v[84:85]
	v_pk_fma_f32 v[92:93], v[92:93], v[168:169], v[136:137]
	v_pk_fma_f32 v[92:93], v[172:173], v[160:161], v[92:93]
	v_pk_fma_f32 v[92:93], v[174:175], v[152:153], v[92:93]
	v_pk_fma_f32 v[92:93], v[212:213], v[144:145], v[92:93]
	v_pk_mul_f32 v[214:215], v[92:93], s[16:17]
	v_pk_mul_f32 v[242:243], v[84:85], s[16:17]
	v_pk_mul_f32 v[244:245], v[76:77], s[16:17]
	v_pk_mul_f32 v[246:247], v[68:69], s[16:17]
	v_exp_f32_e32 v214, v214
	v_exp_f32_e32 v215, v215
	v_exp_f32_e32 v242, v242
	v_exp_f32_e32 v243, v243
	v_exp_f32_e32 v244, v244
	v_exp_f32_e32 v245, v245
	v_exp_f32_e32 v246, v246
	v_exp_f32_e32 v247, v247
	v_pk_add_f32 v[214:215], v[214:215], 1.0 op_sel_hi:[1,0]
	v_pk_add_f32 v[242:243], v[242:243], 1.0 op_sel_hi:[1,0]
	v_pk_add_f32 v[244:245], v[244:245], 1.0 op_sel_hi:[1,0]
	v_pk_add_f32 v[246:247], v[246:247], 1.0 op_sel_hi:[1,0]
	v_rcp_f32_e32 v214, v214
	v_rcp_f32_e32 v215, v215
	v_rcp_f32_e32 v242, v242
	v_rcp_f32_e32 v243, v243
	v_rcp_f32_e32 v244, v244
	v_rcp_f32_e32 v245, v245
	v_rcp_f32_e32 v246, v246
	v_rcp_f32_e32 v247, v247
	v_pk_mul_f32 v[92:93], v[92:93], v[214:215]
	v_pk_mul_f32 v[84:85], v[84:85], v[242:243]
	v_pk_mul_f32 v[76:77], v[76:77], v[244:245]
	v_pk_mul_f32 v[68:69], v[68:69], v[246:247]
	v_cvt_pk_bf16_f32 v98, v92, v93
	v_cvt_pk_bf16_f32 v90, v84, v85
	v_cvt_pk_bf16_f32 v82, v76, v77
	v_cvt_pk_bf16_f32 v74, v68, v69
	v_mov_b32_dpp v172, v70 row_shr:1 row_mask:0xf bank_mask:0xf bound_ctrl:1
	v_mov_b32_dpp v173, v71 row_shr:1 row_mask:0xf bank_mask:0xf bound_ctrl:1
	v_mov_b32_dpp v174, v78 row_shr:1 row_mask:0xf bank_mask:0xf bound_ctrl:1
	v_mov_b32_dpp v175, v79 row_shr:1 row_mask:0xf bank_mask:0xf bound_ctrl:1
	v_mov_b32_dpp v212, v86 row_shr:1 row_mask:0xf bank_mask:0xf bound_ctrl:1
	v_mov_b32_dpp v213, v87 row_shr:1 row_mask:0xf bank_mask:0xf bound_ctrl:1
	v_pk_fma_f32 v[70:71], v[70:71], v[170:171], v[138:139]
	v_pk_fma_f32 v[70:71], v[78:79], v[162:163], v[70:71]
	v_pk_fma_f32 v[70:71], v[86:87], v[154:155], v[70:71]
	v_pk_fma_f32 v[70:71], v[94:95], v[146:147], v[70:71]
	v_pk_fma_f32 v[78:79], v[78:79], v[170:171], v[138:139]
	v_pk_fma_f32 v[78:79], v[86:87], v[162:163], v[78:79]
	v_pk_fma_f32 v[78:79], v[94:95], v[154:155], v[78:79]
	v_pk_fma_f32 v[78:79], v[172:173], v[146:147], v[78:79]
	v_pk_fma_f32 v[86:87], v[86:87], v[170:171], v[138:139]
	v_pk_fma_f32 v[86:87], v[94:95], v[162:163], v[86:87]
	v_pk_fma_f32 v[86:87], v[172:173], v[154:155], v[86:87]
	v_pk_fma_f32 v[86:87], v[174:175], v[146:147], v[86:87]
	v_pk_fma_f32 v[94:95], v[94:95], v[170:171], v[138:139]
	v_pk_fma_f32 v[94:95], v[172:173], v[162:163], v[94:95]
	v_pk_fma_f32 v[94:95], v[174:175], v[154:155], v[94:95]
	v_pk_fma_f32 v[94:95], v[212:213], v[146:147], v[94:95]
	v_pk_mul_f32 v[214:215], v[94:95], s[16:17]
	v_pk_mul_f32 v[242:243], v[86:87], s[16:17]
	v_pk_mul_f32 v[244:245], v[78:79], s[16:17]
	v_pk_mul_f32 v[246:247], v[70:71], s[16:17]
	v_exp_f32_e32 v214, v214
	v_exp_f32_e32 v215, v215
	v_exp_f32_e32 v242, v242
	v_exp_f32_e32 v243, v243
	v_exp_f32_e32 v244, v244
	v_exp_f32_e32 v245, v245
	v_exp_f32_e32 v246, v246
	v_exp_f32_e32 v247, v247
	v_pk_add_f32 v[214:215], v[214:215], 1.0 op_sel_hi:[1,0]
	v_pk_add_f32 v[242:243], v[242:243], 1.0 op_sel_hi:[1,0]
	v_pk_add_f32 v[244:245], v[244:245], 1.0 op_sel_hi:[1,0]
	v_pk_add_f32 v[246:247], v[246:247], 1.0 op_sel_hi:[1,0]
	v_rcp_f32_e32 v214, v214
	v_rcp_f32_e32 v215, v215
	v_rcp_f32_e32 v242, v242
	v_rcp_f32_e32 v243, v243
	v_rcp_f32_e32 v244, v244
	v_rcp_f32_e32 v245, v245
	v_rcp_f32_e32 v246, v246
	v_rcp_f32_e32 v247, v247
	v_pk_mul_f32 v[94:95], v[94:95], v[214:215]
	v_pk_mul_f32 v[86:87], v[86:87], v[242:243]
	v_pk_mul_f32 v[78:79], v[78:79], v[244:245]
	v_pk_mul_f32 v[70:71], v[70:71], v[246:247]
	v_cvt_pk_bf16_f32 v99, v94, v95
	v_cvt_pk_bf16_f32 v91, v86, v87
	v_cvt_pk_bf16_f32 v83, v78, v79
	v_cvt_pk_bf16_f32 v75, v70, v71
	s_add_i32 s0, s44, 128
	s_mul_i32 s0, s0, s29
	s_add_u32 s0, s4, s0
	s_addc_u32 s1, s5, 0
	global_store_dwordx4 v198, v[96:99], s[0:1]
	s_add_i32 s0, s44, 129
	s_mul_i32 s0, s0, s29
	s_add_u32 s0, s4, s0
	s_addc_u32 s1, s5, 0
	global_store_dwordx4 v198, v[88:91], s[0:1]
	s_add_i32 s0, s44, 130
	s_mul_i32 s0, s0, s29
	s_add_u32 s0, s4, s0
	s_addc_u32 s1, s5, 0
	global_store_dwordx4 v198, v[80:83], s[0:1]
	s_add_i32 s0, s44, 131
	s_mul_i32 s0, s0, s29
	s_add_u32 s0, s4, s0
	s_addc_u32 s1, s5, 0
	global_store_dwordx4 v198, v[72:75], s[0:1]
	s_waitcnt vmcnt(4)
	v_mov_b32_dpp v172, v40 row_shr:1 row_mask:0xf bank_mask:0xf bound_ctrl:1
	v_mov_b32_dpp v173, v41 row_shr:1 row_mask:0xf bank_mask:0xf bound_ctrl:1
	v_mov_b32_dpp v174, v48 row_shr:1 row_mask:0xf bank_mask:0xf bound_ctrl:1
	v_mov_b32_dpp v175, v49 row_shr:1 row_mask:0xf bank_mask:0xf bound_ctrl:1
	v_mov_b32_dpp v212, v56 row_shr:1 row_mask:0xf bank_mask:0xf bound_ctrl:1
	v_mov_b32_dpp v213, v57 row_shr:1 row_mask:0xf bank_mask:0xf bound_ctrl:1
	v_pk_fma_f32 v[40:41], v[40:41], v[204:205], v[128:129]
	v_pk_fma_f32 v[40:41], v[48:49], v[104:105], v[40:41]
	v_pk_fma_f32 v[40:41], v[56:57], v[112:113], v[40:41]
	v_pk_fma_f32 v[40:41], v[64:65], v[120:121], v[40:41]
	v_pk_fma_f32 v[48:49], v[48:49], v[204:205], v[128:129]
	v_pk_fma_f32 v[48:49], v[56:57], v[104:105], v[48:49]
	v_pk_fma_f32 v[48:49], v[64:65], v[112:113], v[48:49]
	v_pk_fma_f32 v[48:49], v[172:173], v[120:121], v[48:49]
	v_pk_fma_f32 v[56:57], v[56:57], v[204:205], v[128:129]
	v_pk_fma_f32 v[56:57], v[64:65], v[104:105], v[56:57]
	v_pk_fma_f32 v[56:57], v[172:173], v[112:113], v[56:57]
	v_pk_fma_f32 v[56:57], v[174:175], v[120:121], v[56:57]
	v_pk_fma_f32 v[64:65], v[64:65], v[204:205], v[128:129]
	v_pk_fma_f32 v[64:65], v[172:173], v[104:105], v[64:65]
	v_pk_fma_f32 v[64:65], v[174:175], v[112:113], v[64:65]
	v_pk_fma_f32 v[64:65], v[212:213], v[120:121], v[64:65]
	v_pk_mul_f32 v[214:215], v[64:65], s[16:17]
	v_pk_mul_f32 v[242:243], v[56:57], s[16:17]
	v_pk_mul_f32 v[244:245], v[48:49], s[16:17]
	v_pk_mul_f32 v[246:247], v[40:41], s[16:17]
	v_exp_f32_e32 v214, v214
	v_exp_f32_e32 v215, v215
	v_exp_f32_e32 v242, v242
	v_exp_f32_e32 v243, v243
	v_exp_f32_e32 v244, v244
	v_exp_f32_e32 v245, v245
	v_exp_f32_e32 v246, v246
	v_exp_f32_e32 v247, v247
	v_pk_add_f32 v[214:215], v[214:215], 1.0 op_sel_hi:[1,0]
	v_pk_add_f32 v[242:243], v[242:243], 1.0 op_sel_hi:[1,0]
	v_pk_add_f32 v[244:245], v[244:245], 1.0 op_sel_hi:[1,0]
	v_pk_add_f32 v[246:247], v[246:247], 1.0 op_sel_hi:[1,0]
	v_rcp_f32_e32 v214, v214
	v_rcp_f32_e32 v215, v215
	v_rcp_f32_e32 v242, v242
	v_rcp_f32_e32 v243, v243
	v_rcp_f32_e32 v244, v244
	v_rcp_f32_e32 v245, v245
	v_rcp_f32_e32 v246, v246
	v_rcp_f32_e32 v247, v247
	v_pk_mul_f32 v[64:65], v[64:65], v[214:215]
	v_pk_mul_f32 v[56:57], v[56:57], v[242:243]
	v_pk_mul_f32 v[48:49], v[48:49], v[244:245]
	v_pk_mul_f32 v[40:41], v[40:41], v[246:247]
	v_cvt_pk_bf16_f32 v64, v64, v65
	v_cvt_pk_bf16_f32 v56, v56, v57
	v_cvt_pk_bf16_f32 v48, v48, v49
	v_cvt_pk_bf16_f32 v40, v40, v41
	v_mov_b32_dpp v172, v42 row_shr:1 row_mask:0xf bank_mask:0xf bound_ctrl:1
	v_mov_b32_dpp v173, v43 row_shr:1 row_mask:0xf bank_mask:0xf bound_ctrl:1
	v_mov_b32_dpp v174, v50 row_shr:1 row_mask:0xf bank_mask:0xf bound_ctrl:1
	v_mov_b32_dpp v175, v51 row_shr:1 row_mask:0xf bank_mask:0xf bound_ctrl:1
	v_mov_b32_dpp v212, v58 row_shr:1 row_mask:0xf bank_mask:0xf bound_ctrl:1
	v_mov_b32_dpp v213, v59 row_shr:1 row_mask:0xf bank_mask:0xf bound_ctrl:1
	v_pk_fma_f32 v[42:43], v[42:43], v[206:207], v[130:131]
	v_pk_fma_f32 v[42:43], v[50:51], v[106:107], v[42:43]
	v_pk_fma_f32 v[42:43], v[58:59], v[114:115], v[42:43]
	v_pk_fma_f32 v[42:43], v[66:67], v[122:123], v[42:43]
	v_pk_fma_f32 v[50:51], v[50:51], v[206:207], v[130:131]
	v_pk_fma_f32 v[50:51], v[58:59], v[106:107], v[50:51]
	v_pk_fma_f32 v[50:51], v[66:67], v[114:115], v[50:51]
	v_pk_fma_f32 v[50:51], v[172:173], v[122:123], v[50:51]
	v_pk_fma_f32 v[58:59], v[58:59], v[206:207], v[130:131]
	v_pk_fma_f32 v[58:59], v[66:67], v[106:107], v[58:59]
	v_pk_fma_f32 v[58:59], v[172:173], v[114:115], v[58:59]
	v_pk_fma_f32 v[58:59], v[174:175], v[122:123], v[58:59]
	v_pk_fma_f32 v[66:67], v[66:67], v[206:207], v[130:131]
	v_pk_fma_f32 v[66:67], v[172:173], v[106:107], v[66:67]
	v_pk_fma_f32 v[66:67], v[174:175], v[114:115], v[66:67]
	v_pk_fma_f32 v[66:67], v[212:213], v[122:123], v[66:67]
	v_pk_mul_f32 v[214:215], v[66:67], s[16:17]
	v_pk_mul_f32 v[242:243], v[58:59], s[16:17]
	v_pk_mul_f32 v[244:245], v[50:51], s[16:17]
	v_pk_mul_f32 v[246:247], v[42:43], s[16:17]
	v_exp_f32_e32 v214, v214
	v_exp_f32_e32 v215, v215
	v_exp_f32_e32 v242, v242
	v_exp_f32_e32 v243, v243
	v_exp_f32_e32 v244, v244
	v_exp_f32_e32 v245, v245
	v_exp_f32_e32 v246, v246
	v_exp_f32_e32 v247, v247
	v_pk_add_f32 v[214:215], v[214:215], 1.0 op_sel_hi:[1,0]
	v_pk_add_f32 v[242:243], v[242:243], 1.0 op_sel_hi:[1,0]
	v_pk_add_f32 v[244:245], v[244:245], 1.0 op_sel_hi:[1,0]
	v_pk_add_f32 v[246:247], v[246:247], 1.0 op_sel_hi:[1,0]
	v_rcp_f32_e32 v214, v214
	v_rcp_f32_e32 v215, v215
	v_rcp_f32_e32 v242, v242
	v_rcp_f32_e32 v243, v243
	v_rcp_f32_e32 v244, v244
	v_rcp_f32_e32 v245, v245
	v_rcp_f32_e32 v246, v246
	v_rcp_f32_e32 v247, v247
	v_pk_mul_f32 v[66:67], v[66:67], v[214:215]
	v_pk_mul_f32 v[58:59], v[58:59], v[242:243]
	v_pk_mul_f32 v[50:51], v[50:51], v[244:245]
	v_pk_mul_f32 v[42:43], v[42:43], v[246:247]
	v_cvt_pk_bf16_f32 v65, v66, v67
	v_cvt_pk_bf16_f32 v57, v58, v59
	v_cvt_pk_bf16_f32 v49, v50, v51
	v_cvt_pk_bf16_f32 v41, v42, v43
	v_mov_b32_dpp v172, v36 row_shr:1 row_mask:0xf bank_mask:0xf bound_ctrl:1
	v_mov_b32_dpp v173, v37 row_shr:1 row_mask:0xf bank_mask:0xf bound_ctrl:1
	v_mov_b32_dpp v174, v44 row_shr:1 row_mask:0xf bank_mask:0xf bound_ctrl:1
	v_mov_b32_dpp v175, v45 row_shr:1 row_mask:0xf bank_mask:0xf bound_ctrl:1
	v_mov_b32_dpp v212, v52 row_shr:1 row_mask:0xf bank_mask:0xf bound_ctrl:1
	v_mov_b32_dpp v213, v53 row_shr:1 row_mask:0xf bank_mask:0xf bound_ctrl:1
	v_pk_fma_f32 v[36:37], v[36:37], v[208:209], v[124:125]
	v_pk_fma_f32 v[36:37], v[44:45], v[100:101], v[36:37]
	v_pk_fma_f32 v[36:37], v[52:53], v[108:109], v[36:37]
	v_pk_fma_f32 v[36:37], v[60:61], v[116:117], v[36:37]
	v_pk_fma_f32 v[44:45], v[44:45], v[208:209], v[124:125]
	v_pk_fma_f32 v[44:45], v[52:53], v[100:101], v[44:45]
	v_pk_fma_f32 v[44:45], v[60:61], v[108:109], v[44:45]
	v_pk_fma_f32 v[44:45], v[172:173], v[116:117], v[44:45]
	v_pk_fma_f32 v[52:53], v[52:53], v[208:209], v[124:125]
	v_pk_fma_f32 v[52:53], v[60:61], v[100:101], v[52:53]
	v_pk_fma_f32 v[52:53], v[172:173], v[108:109], v[52:53]
	v_pk_fma_f32 v[52:53], v[174:175], v[116:117], v[52:53]
	v_pk_fma_f32 v[60:61], v[60:61], v[208:209], v[124:125]
	v_pk_fma_f32 v[60:61], v[172:173], v[100:101], v[60:61]
	v_pk_fma_f32 v[60:61], v[174:175], v[108:109], v[60:61]
	v_pk_fma_f32 v[60:61], v[212:213], v[116:117], v[60:61]
	v_pk_mul_f32 v[214:215], v[60:61], s[16:17]
	v_pk_mul_f32 v[242:243], v[52:53], s[16:17]
	v_pk_mul_f32 v[244:245], v[44:45], s[16:17]
	v_pk_mul_f32 v[246:247], v[36:37], s[16:17]
	v_exp_f32_e32 v214, v214
	v_exp_f32_e32 v215, v215
	v_exp_f32_e32 v242, v242
	v_exp_f32_e32 v243, v243
	v_exp_f32_e32 v244, v244
	v_exp_f32_e32 v245, v245
	v_exp_f32_e32 v246, v246
	v_exp_f32_e32 v247, v247
	v_pk_add_f32 v[214:215], v[214:215], 1.0 op_sel_hi:[1,0]
	v_pk_add_f32 v[242:243], v[242:243], 1.0 op_sel_hi:[1,0]
	v_pk_add_f32 v[244:245], v[244:245], 1.0 op_sel_hi:[1,0]
	v_pk_add_f32 v[246:247], v[246:247], 1.0 op_sel_hi:[1,0]
	v_rcp_f32_e32 v214, v214
	v_rcp_f32_e32 v215, v215
	v_rcp_f32_e32 v242, v242
	v_rcp_f32_e32 v243, v243
	v_rcp_f32_e32 v244, v244
	v_rcp_f32_e32 v245, v245
	v_rcp_f32_e32 v246, v246
	v_rcp_f32_e32 v247, v247
	v_pk_mul_f32 v[60:61], v[60:61], v[214:215]
	v_pk_mul_f32 v[52:53], v[52:53], v[242:243]
	v_pk_mul_f32 v[44:45], v[44:45], v[244:245]
	v_pk_mul_f32 v[36:37], v[36:37], v[246:247]
	v_cvt_pk_bf16_f32 v66, v60, v61
	v_cvt_pk_bf16_f32 v58, v52, v53
	v_cvt_pk_bf16_f32 v50, v44, v45
	v_cvt_pk_bf16_f32 v42, v36, v37
	v_mov_b32_dpp v172, v38 row_shr:1 row_mask:0xf bank_mask:0xf bound_ctrl:1
	v_mov_b32_dpp v173, v39 row_shr:1 row_mask:0xf bank_mask:0xf bound_ctrl:1
	v_mov_b32_dpp v174, v46 row_shr:1 row_mask:0xf bank_mask:0xf bound_ctrl:1
	v_mov_b32_dpp v175, v47 row_shr:1 row_mask:0xf bank_mask:0xf bound_ctrl:1
	v_mov_b32_dpp v212, v54 row_shr:1 row_mask:0xf bank_mask:0xf bound_ctrl:1
	v_mov_b32_dpp v213, v55 row_shr:1 row_mask:0xf bank_mask:0xf bound_ctrl:1
	v_pk_fma_f32 v[38:39], v[38:39], v[210:211], v[126:127]
	v_pk_fma_f32 v[38:39], v[46:47], v[102:103], v[38:39]
	v_pk_fma_f32 v[38:39], v[54:55], v[110:111], v[38:39]
	v_pk_fma_f32 v[38:39], v[62:63], v[118:119], v[38:39]
	v_pk_fma_f32 v[46:47], v[46:47], v[210:211], v[126:127]
	v_pk_fma_f32 v[46:47], v[54:55], v[102:103], v[46:47]
	v_pk_fma_f32 v[46:47], v[62:63], v[110:111], v[46:47]
	v_pk_fma_f32 v[46:47], v[172:173], v[118:119], v[46:47]
	v_pk_fma_f32 v[54:55], v[54:55], v[210:211], v[126:127]
	v_pk_fma_f32 v[54:55], v[62:63], v[102:103], v[54:55]
	v_pk_fma_f32 v[54:55], v[172:173], v[110:111], v[54:55]
	v_pk_fma_f32 v[54:55], v[174:175], v[118:119], v[54:55]
	v_pk_fma_f32 v[62:63], v[62:63], v[210:211], v[126:127]
	v_pk_fma_f32 v[62:63], v[172:173], v[102:103], v[62:63]
	v_pk_fma_f32 v[62:63], v[174:175], v[110:111], v[62:63]
	v_pk_fma_f32 v[62:63], v[212:213], v[118:119], v[62:63]
	v_pk_mul_f32 v[214:215], v[62:63], s[16:17]
	v_pk_mul_f32 v[242:243], v[54:55], s[16:17]
	v_pk_mul_f32 v[244:245], v[46:47], s[16:17]
	v_pk_mul_f32 v[246:247], v[38:39], s[16:17]
	v_exp_f32_e32 v214, v214
	v_exp_f32_e32 v215, v215
	v_exp_f32_e32 v242, v242
	v_exp_f32_e32 v243, v243
	v_exp_f32_e32 v244, v244
	v_exp_f32_e32 v245, v245
	v_exp_f32_e32 v246, v246
	v_exp_f32_e32 v247, v247
	v_pk_add_f32 v[214:215], v[214:215], 1.0 op_sel_hi:[1,0]
	v_pk_add_f32 v[242:243], v[242:243], 1.0 op_sel_hi:[1,0]
	v_pk_add_f32 v[244:245], v[244:245], 1.0 op_sel_hi:[1,0]
	v_pk_add_f32 v[246:247], v[246:247], 1.0 op_sel_hi:[1,0]
	v_rcp_f32_e32 v214, v214
	v_rcp_f32_e32 v215, v215
	v_rcp_f32_e32 v242, v242
	v_rcp_f32_e32 v243, v243
	v_rcp_f32_e32 v244, v244
	v_rcp_f32_e32 v245, v245
	v_rcp_f32_e32 v246, v246
	v_rcp_f32_e32 v247, v247
	v_pk_mul_f32 v[62:63], v[62:63], v[214:215]
	v_pk_mul_f32 v[54:55], v[54:55], v[242:243]
	v_pk_mul_f32 v[46:47], v[46:47], v[244:245]
	v_pk_mul_f32 v[38:39], v[38:39], v[246:247]
	v_cvt_pk_bf16_f32 v67, v62, v63
	v_cvt_pk_bf16_f32 v59, v54, v55
	v_cvt_pk_bf16_f32 v51, v46, v47
	v_cvt_pk_bf16_f32 v43, v38, v39
	s_add_i32 s0, s44, 0
	s_mul_i32 s0, s0, s29
	s_add_u32 s0, s4, s0
	s_addc_u32 s1, s5, 0
	global_store_dwordx4 v198, v[64:67], s[0:1] offset:256
	s_add_i32 s0, s44, 1
	s_mul_i32 s0, s0, s29
	s_add_u32 s0, s4, s0
	s_addc_u32 s1, s5, 0
	global_store_dwordx4 v198, v[56:59], s[0:1] offset:256
	s_add_i32 s0, s44, 2
	s_mul_i32 s0, s0, s29
	s_add_u32 s0, s4, s0
	s_addc_u32 s1, s5, 0
	global_store_dwordx4 v198, v[48:51], s[0:1] offset:256
	s_add_i32 s0, s44, 3
	s_mul_i32 s0, s0, s29
	s_add_u32 s0, s4, s0
	s_addc_u32 s1, s5, 0
	global_store_dwordx4 v198, v[40:43], s[0:1] offset:256
	v_mov_b32_dpp v172, v8 row_shr:1 row_mask:0xf bank_mask:0xf bound_ctrl:1
	v_mov_b32_dpp v173, v9 row_shr:1 row_mask:0xf bank_mask:0xf bound_ctrl:1
	v_mov_b32_dpp v174, v16 row_shr:1 row_mask:0xf bank_mask:0xf bound_ctrl:1
	v_mov_b32_dpp v175, v17 row_shr:1 row_mask:0xf bank_mask:0xf bound_ctrl:1
	v_mov_b32_dpp v212, v24 row_shr:1 row_mask:0xf bank_mask:0xf bound_ctrl:1
	v_mov_b32_dpp v213, v25 row_shr:1 row_mask:0xf bank_mask:0xf bound_ctrl:1
	v_pk_fma_f32 v[8:9], v[8:9], v[204:205], v[128:129]
	v_pk_fma_f32 v[8:9], v[16:17], v[104:105], v[8:9]
	v_pk_fma_f32 v[8:9], v[24:25], v[112:113], v[8:9]
	v_pk_fma_f32 v[8:9], v[32:33], v[120:121], v[8:9]
	v_pk_fma_f32 v[16:17], v[16:17], v[204:205], v[128:129]
	v_pk_fma_f32 v[16:17], v[24:25], v[104:105], v[16:17]
	v_pk_fma_f32 v[16:17], v[32:33], v[112:113], v[16:17]
	v_pk_fma_f32 v[16:17], v[172:173], v[120:121], v[16:17]
	v_pk_fma_f32 v[24:25], v[24:25], v[204:205], v[128:129]
	v_pk_fma_f32 v[24:25], v[32:33], v[104:105], v[24:25]
	v_pk_fma_f32 v[24:25], v[172:173], v[112:113], v[24:25]
	v_pk_fma_f32 v[24:25], v[174:175], v[120:121], v[24:25]
	v_pk_fma_f32 v[32:33], v[32:33], v[204:205], v[128:129]
	v_pk_fma_f32 v[32:33], v[172:173], v[104:105], v[32:33]
	v_pk_fma_f32 v[32:33], v[174:175], v[112:113], v[32:33]
	v_pk_fma_f32 v[32:33], v[212:213], v[120:121], v[32:33]
	v_pk_mul_f32 v[214:215], v[32:33], s[16:17]
	v_pk_mul_f32 v[242:243], v[24:25], s[16:17]
	v_pk_mul_f32 v[244:245], v[16:17], s[16:17]
	v_pk_mul_f32 v[246:247], v[8:9], s[16:17]
	v_exp_f32_e32 v214, v214
	v_exp_f32_e32 v215, v215
	v_exp_f32_e32 v242, v242
	v_exp_f32_e32 v243, v243
	v_exp_f32_e32 v244, v244
	v_exp_f32_e32 v245, v245
	v_exp_f32_e32 v246, v246
	v_exp_f32_e32 v247, v247
	v_pk_add_f32 v[214:215], v[214:215], 1.0 op_sel_hi:[1,0]
	v_pk_add_f32 v[242:243], v[242:243], 1.0 op_sel_hi:[1,0]
	v_pk_add_f32 v[244:245], v[244:245], 1.0 op_sel_hi:[1,0]
	v_pk_add_f32 v[246:247], v[246:247], 1.0 op_sel_hi:[1,0]
	v_rcp_f32_e32 v214, v214
	v_rcp_f32_e32 v215, v215
	v_rcp_f32_e32 v242, v242
	v_rcp_f32_e32 v243, v243
	v_rcp_f32_e32 v244, v244
	v_rcp_f32_e32 v245, v245
	v_rcp_f32_e32 v246, v246
	v_rcp_f32_e32 v247, v247
	v_pk_mul_f32 v[32:33], v[32:33], v[214:215]
	v_pk_mul_f32 v[24:25], v[24:25], v[242:243]
	v_pk_mul_f32 v[16:17], v[16:17], v[244:245]
	v_pk_mul_f32 v[8:9], v[8:9], v[246:247]
	v_cvt_pk_bf16_f32 v32, v32, v33
	v_cvt_pk_bf16_f32 v24, v24, v25
	v_cvt_pk_bf16_f32 v16, v16, v17
	v_cvt_pk_bf16_f32 v8, v8, v9
	v_mov_b32_dpp v172, v10 row_shr:1 row_mask:0xf bank_mask:0xf bound_ctrl:1
	v_mov_b32_dpp v173, v11 row_shr:1 row_mask:0xf bank_mask:0xf bound_ctrl:1
	v_mov_b32_dpp v174, v18 row_shr:1 row_mask:0xf bank_mask:0xf bound_ctrl:1
	v_mov_b32_dpp v175, v19 row_shr:1 row_mask:0xf bank_mask:0xf bound_ctrl:1
	v_mov_b32_dpp v212, v26 row_shr:1 row_mask:0xf bank_mask:0xf bound_ctrl:1
	v_mov_b32_dpp v213, v27 row_shr:1 row_mask:0xf bank_mask:0xf bound_ctrl:1
	v_pk_fma_f32 v[10:11], v[10:11], v[206:207], v[130:131]
	v_pk_fma_f32 v[10:11], v[18:19], v[106:107], v[10:11]
	v_pk_fma_f32 v[10:11], v[26:27], v[114:115], v[10:11]
	v_pk_fma_f32 v[10:11], v[34:35], v[122:123], v[10:11]
	v_pk_fma_f32 v[18:19], v[18:19], v[206:207], v[130:131]
	v_pk_fma_f32 v[18:19], v[26:27], v[106:107], v[18:19]
	v_pk_fma_f32 v[18:19], v[34:35], v[114:115], v[18:19]
	v_pk_fma_f32 v[18:19], v[172:173], v[122:123], v[18:19]
	v_pk_fma_f32 v[26:27], v[26:27], v[206:207], v[130:131]
	v_pk_fma_f32 v[26:27], v[34:35], v[106:107], v[26:27]
	v_pk_fma_f32 v[26:27], v[172:173], v[114:115], v[26:27]
	v_pk_fma_f32 v[26:27], v[174:175], v[122:123], v[26:27]
	v_pk_fma_f32 v[34:35], v[34:35], v[206:207], v[130:131]
	v_pk_fma_f32 v[34:35], v[172:173], v[106:107], v[34:35]
	v_pk_fma_f32 v[34:35], v[174:175], v[114:115], v[34:35]
	v_pk_fma_f32 v[34:35], v[212:213], v[122:123], v[34:35]
	v_pk_mul_f32 v[214:215], v[34:35], s[16:17]
	v_pk_mul_f32 v[242:243], v[26:27], s[16:17]
	v_pk_mul_f32 v[244:245], v[18:19], s[16:17]
	v_pk_mul_f32 v[246:247], v[10:11], s[16:17]
	v_exp_f32_e32 v214, v214
	v_exp_f32_e32 v215, v215
	v_exp_f32_e32 v242, v242
	v_exp_f32_e32 v243, v243
	v_exp_f32_e32 v244, v244
	v_exp_f32_e32 v245, v245
	v_exp_f32_e32 v246, v246
	v_exp_f32_e32 v247, v247
	v_pk_add_f32 v[214:215], v[214:215], 1.0 op_sel_hi:[1,0]
	v_pk_add_f32 v[242:243], v[242:243], 1.0 op_sel_hi:[1,0]
	v_pk_add_f32 v[244:245], v[244:245], 1.0 op_sel_hi:[1,0]
	v_pk_add_f32 v[246:247], v[246:247], 1.0 op_sel_hi:[1,0]
	v_rcp_f32_e32 v214, v214
	v_rcp_f32_e32 v215, v215
	v_rcp_f32_e32 v242, v242
	v_rcp_f32_e32 v243, v243
	v_rcp_f32_e32 v244, v244
	v_rcp_f32_e32 v245, v245
	v_rcp_f32_e32 v246, v246
	v_rcp_f32_e32 v247, v247
	v_pk_mul_f32 v[34:35], v[34:35], v[214:215]
	v_pk_mul_f32 v[26:27], v[26:27], v[242:243]
	v_pk_mul_f32 v[18:19], v[18:19], v[244:245]
	v_pk_mul_f32 v[10:11], v[10:11], v[246:247]
	v_cvt_pk_bf16_f32 v33, v34, v35
	v_cvt_pk_bf16_f32 v25, v26, v27
	v_cvt_pk_bf16_f32 v17, v18, v19
	v_cvt_pk_bf16_f32 v9, v10, v11
	v_mov_b32_dpp v172, v4 row_shr:1 row_mask:0xf bank_mask:0xf bound_ctrl:1
	v_mov_b32_dpp v173, v5 row_shr:1 row_mask:0xf bank_mask:0xf bound_ctrl:1
	v_mov_b32_dpp v174, v12 row_shr:1 row_mask:0xf bank_mask:0xf bound_ctrl:1
	v_mov_b32_dpp v175, v13 row_shr:1 row_mask:0xf bank_mask:0xf bound_ctrl:1
	v_mov_b32_dpp v212, v20 row_shr:1 row_mask:0xf bank_mask:0xf bound_ctrl:1
	v_mov_b32_dpp v213, v21 row_shr:1 row_mask:0xf bank_mask:0xf bound_ctrl:1
	v_pk_fma_f32 v[4:5], v[4:5], v[208:209], v[124:125]
	v_pk_fma_f32 v[4:5], v[12:13], v[100:101], v[4:5]
	v_pk_fma_f32 v[4:5], v[20:21], v[108:109], v[4:5]
	v_pk_fma_f32 v[4:5], v[28:29], v[116:117], v[4:5]
	v_pk_fma_f32 v[12:13], v[12:13], v[208:209], v[124:125]
	v_pk_fma_f32 v[12:13], v[20:21], v[100:101], v[12:13]
	v_pk_fma_f32 v[12:13], v[28:29], v[108:109], v[12:13]
	v_pk_fma_f32 v[12:13], v[172:173], v[116:117], v[12:13]
	v_pk_fma_f32 v[20:21], v[20:21], v[208:209], v[124:125]
	v_pk_fma_f32 v[20:21], v[28:29], v[100:101], v[20:21]
	v_pk_fma_f32 v[20:21], v[172:173], v[108:109], v[20:21]
	v_pk_fma_f32 v[20:21], v[174:175], v[116:117], v[20:21]
	v_pk_fma_f32 v[28:29], v[28:29], v[208:209], v[124:125]
	v_pk_fma_f32 v[28:29], v[172:173], v[100:101], v[28:29]
	v_pk_fma_f32 v[28:29], v[174:175], v[108:109], v[28:29]
	v_pk_fma_f32 v[28:29], v[212:213], v[116:117], v[28:29]
	v_pk_mul_f32 v[214:215], v[28:29], s[16:17]
	v_pk_mul_f32 v[242:243], v[20:21], s[16:17]
	v_pk_mul_f32 v[244:245], v[12:13], s[16:17]
	v_pk_mul_f32 v[246:247], v[4:5], s[16:17]
	v_exp_f32_e32 v214, v214
	v_exp_f32_e32 v215, v215
	v_exp_f32_e32 v242, v242
	v_exp_f32_e32 v243, v243
	v_exp_f32_e32 v244, v244
	v_exp_f32_e32 v245, v245
	v_exp_f32_e32 v246, v246
	v_exp_f32_e32 v247, v247
	v_pk_add_f32 v[214:215], v[214:215], 1.0 op_sel_hi:[1,0]
	v_pk_add_f32 v[242:243], v[242:243], 1.0 op_sel_hi:[1,0]
	v_pk_add_f32 v[244:245], v[244:245], 1.0 op_sel_hi:[1,0]
	v_pk_add_f32 v[246:247], v[246:247], 1.0 op_sel_hi:[1,0]
	v_rcp_f32_e32 v214, v214
	v_rcp_f32_e32 v215, v215
	v_rcp_f32_e32 v242, v242
	v_rcp_f32_e32 v243, v243
	v_rcp_f32_e32 v244, v244
	v_rcp_f32_e32 v245, v245
	v_rcp_f32_e32 v246, v246
	v_rcp_f32_e32 v247, v247
	v_pk_mul_f32 v[28:29], v[28:29], v[214:215]
	v_pk_mul_f32 v[20:21], v[20:21], v[242:243]
	v_pk_mul_f32 v[12:13], v[12:13], v[244:245]
	v_pk_mul_f32 v[4:5], v[4:5], v[246:247]
	v_cvt_pk_bf16_f32 v34, v28, v29
	v_cvt_pk_bf16_f32 v26, v20, v21
	v_cvt_pk_bf16_f32 v18, v12, v13
	v_cvt_pk_bf16_f32 v10, v4, v5
	v_mov_b32_dpp v172, v6 row_shr:1 row_mask:0xf bank_mask:0xf bound_ctrl:1
	v_mov_b32_dpp v173, v7 row_shr:1 row_mask:0xf bank_mask:0xf bound_ctrl:1
	v_mov_b32_dpp v174, v14 row_shr:1 row_mask:0xf bank_mask:0xf bound_ctrl:1
	v_mov_b32_dpp v175, v15 row_shr:1 row_mask:0xf bank_mask:0xf bound_ctrl:1
	v_mov_b32_dpp v212, v22 row_shr:1 row_mask:0xf bank_mask:0xf bound_ctrl:1
	v_mov_b32_dpp v213, v23 row_shr:1 row_mask:0xf bank_mask:0xf bound_ctrl:1
	v_pk_fma_f32 v[6:7], v[6:7], v[210:211], v[126:127]
	v_pk_fma_f32 v[6:7], v[14:15], v[102:103], v[6:7]
	v_pk_fma_f32 v[6:7], v[22:23], v[110:111], v[6:7]
	v_pk_fma_f32 v[6:7], v[30:31], v[118:119], v[6:7]
	v_pk_fma_f32 v[14:15], v[14:15], v[210:211], v[126:127]
	v_pk_fma_f32 v[14:15], v[22:23], v[102:103], v[14:15]
	v_pk_fma_f32 v[14:15], v[30:31], v[110:111], v[14:15]
	v_pk_fma_f32 v[14:15], v[172:173], v[118:119], v[14:15]
	v_pk_fma_f32 v[22:23], v[22:23], v[210:211], v[126:127]
	v_pk_fma_f32 v[22:23], v[30:31], v[102:103], v[22:23]
	v_pk_fma_f32 v[22:23], v[172:173], v[110:111], v[22:23]
	v_pk_fma_f32 v[22:23], v[174:175], v[118:119], v[22:23]
	v_pk_fma_f32 v[30:31], v[30:31], v[210:211], v[126:127]
	v_pk_fma_f32 v[30:31], v[172:173], v[102:103], v[30:31]
	v_pk_fma_f32 v[30:31], v[174:175], v[110:111], v[30:31]
	v_pk_fma_f32 v[30:31], v[212:213], v[118:119], v[30:31]
	v_pk_mul_f32 v[214:215], v[30:31], s[16:17]
	v_pk_mul_f32 v[242:243], v[22:23], s[16:17]
	v_pk_mul_f32 v[244:245], v[14:15], s[16:17]
	v_pk_mul_f32 v[246:247], v[6:7], s[16:17]
	v_exp_f32_e32 v214, v214
	v_exp_f32_e32 v215, v215
	v_exp_f32_e32 v242, v242
	v_exp_f32_e32 v243, v243
	v_exp_f32_e32 v244, v244
	v_exp_f32_e32 v245, v245
	v_exp_f32_e32 v246, v246
	v_exp_f32_e32 v247, v247
	v_pk_add_f32 v[214:215], v[214:215], 1.0 op_sel_hi:[1,0]
	v_pk_add_f32 v[242:243], v[242:243], 1.0 op_sel_hi:[1,0]
	v_pk_add_f32 v[244:245], v[244:245], 1.0 op_sel_hi:[1,0]
	v_pk_add_f32 v[246:247], v[246:247], 1.0 op_sel_hi:[1,0]
	v_rcp_f32_e32 v214, v214
	v_rcp_f32_e32 v215, v215
	v_rcp_f32_e32 v242, v242
	v_rcp_f32_e32 v243, v243
	v_rcp_f32_e32 v244, v244
	v_rcp_f32_e32 v245, v245
	v_rcp_f32_e32 v246, v246
	v_rcp_f32_e32 v247, v247
	v_pk_mul_f32 v[30:31], v[30:31], v[214:215]
	v_pk_mul_f32 v[22:23], v[22:23], v[242:243]
	v_pk_mul_f32 v[14:15], v[14:15], v[244:245]
	v_pk_mul_f32 v[6:7], v[6:7], v[246:247]
	v_cvt_pk_bf16_f32 v35, v30, v31
	v_cvt_pk_bf16_f32 v27, v22, v23
	v_cvt_pk_bf16_f32 v19, v14, v15
	v_cvt_pk_bf16_f32 v11, v6, v7
	s_add_i32 s0, s44, 128
	s_mul_i32 s0, s0, s29
	s_add_u32 s0, s4, s0
	s_addc_u32 s1, s5, 0
	global_store_dwordx4 v198, v[32:35], s[0:1] offset:256
	s_add_i32 s0, s44, 129
	s_mul_i32 s0, s0, s29
	s_add_u32 s0, s4, s0
	s_addc_u32 s1, s5, 0
	global_store_dwordx4 v198, v[24:27], s[0:1] offset:256
	s_add_i32 s0, s44, 130
	s_mul_i32 s0, s0, s29
	s_add_u32 s0, s4, s0
	s_addc_u32 s1, s5, 0
	global_store_dwordx4 v198, v[16:19], s[0:1] offset:256
	s_add_i32 s0, s44, 131
	s_mul_i32 s0, s0, s29
	s_add_u32 s0, s4, s0
	s_addc_u32 s1, s5, 0
	global_store_dwordx4 v198, v[8:11], s[0:1] offset:256
	v_readlane_b32 s12, v254, 42
	v_readlane_b32 s13, v254, 43
	v_readlane_b32 s14, v254, 44
	v_readlane_b32 s15, v254, 45
	v_readlane_b32 s16, v254, 46
	v_readlane_b32 s17, v254, 47
	v_readlane_b32 s18, v254, 48
	v_readlane_b32 s19, v254, 49
	v_readlane_b32 s20, v254, 50
	v_readlane_b32 s21, v254, 51
	v_readlane_b32 s22, v254, 52
	v_readlane_b32 s23, v254, 53
	v_readlane_b32 s24, v254, 54
	v_readlane_b32 s25, v254, 55
	v_readlane_b32 s26, v254, 56
	v_readlane_b32 s27, v254, 57
	s_mov_b64 s[0:1], -1
	s_branch .LBB0_418
